# sample-item loader: V rows requested together with K rows (one HBM round trip per tile)
# speedup vs baseline: 1.0085x; 1.0026x over previous
; __device__ __forceinline__ unsigned pk2(float lo, float hi) { const bfx2 b = __builtin_convertvector((f32x2){lo, hi}, bfx2); return __builtin_bit_cast(unsigned, b); }
; __device__ __forceinline__ void rms_row_to_bf16(const float* xrow, const float* g, bf16* orow, int lane) {
;     f32x4 v[8]; float s = 0.f;
; #pragma unroll
;     for (int j = 0; j < 4; ++j) { const float* p = xrow + (j * 64 + lane) * 8; v[2 * j] = __builtin_nontemporal_load((const f32x4*)p); v[2 * j + 1] = __builtin_nontemporal_load((const f32x4*)(p + 4));
;         s += (v[2*j].x * v[2*j].x + v[2*j].y * v[2*j].y) + (v[2*j].z * v[2*j].z + v[2*j].w * v[2*j].w) + (v[2*j+1].x * v[2*j+1].x + v[2*j+1].y * v[2*j+1].y) + (v[2*j+1].z * v[2*j+1].z + v[2*j+1].w * v[2*j+1].w); }
;     const float r = 1.0f / sqrtf(wave_sum(s) * (1.0f / D) + RMS_EPS);
; #pragma unroll
;     for (int j = 0; j < 4; ++j) { const int c = (j * 64 + lane) * 8; const f32x4 g0 = *(const f32x4*)(g + c), g1 = *(const f32x4*)(g + c + 4); const f32x4 a = v[2 * j] * r * g0, b = v[2 * j + 1] * r * g1;
;         u32x4 o; o.x = pk2(a.x, a.y); o.y = pk2(a.z, a.w); o.z = pk2(b.x, b.y); o.w = pk2(b.z, b.w); *(u32x4*)(orow + c) = o; }
; __device__ __forceinline__ void p0_prologue(const P& p, Frame& F) {
;     ...
;     for (int m = gw; m < MPAD; m += NGW) {
;         if (m < MT) { const float* xr = m < MP ? p.in[I_XP] + (size_t)m * D : p.in[I_XS] + (size_t)(m - MP) * D; rms_row_to_bf16(xr, p.in[I_F1PRE], H + (size_t)m * D, F.lane); }
.LBB0_249:
	s_add_u32 s2, s54, 0xc2c8000
	s_addc_u32 s3, s55, 0
	v_writelane_b32 v253, s2, 30
	s_cmpk_gt_i32 s12, 0x40ff
	s_nop 0
	v_writelane_b32 v253, s3, 31
	s_cbranch_scc1 .LBB0_258
	v_lshlrev_b32_e32 v2, 3, v116
	v_mov_b32_e32 v5, 0
	v_or_b32_e32 v6, 0x400, v2
	v_lshlrev_b32_e32 v4, 5, v116
	v_or_b32_e32 v8, 0x600, v2
	v_lshl_add_u64 v[34:35], s[74:75], 0, v[4:5]
	v_lshlrev_b32_e32 v4, 2, v6
	v_lshl_add_u64 v[36:37], s[74:75], 0, v[4:5]
	v_lshlrev_b32_e32 v4, 2, v8
	v_readlane_b32 s2, v253, 30
	v_lshl_add_u64 v[38:39], s[74:75], 0, v[4:5]
	v_lshlrev_b32_e32 v4, 4, v116
	v_readlane_b32 s3, v253, 31
	s_ashr_i32 s13, s12, 31
	s_mov_b32 s9, 0
	v_lshl_add_u64 v[40:41], s[2:3], 0, v[4:5]
	v_readlane_b32 s2, v253, 28
	v_readlane_b32 s3, v253, 29
	s_mov_b32 s4, s2
	s_ashr_i32 s5, s2, 31
	s_lshl_b64 s[2:3], s[12:13], 13
	s_add_u32 s6, s60, s2
	v_writelane_b32 v253, s4, 28
	s_addc_u32 s7, s61, s3
	s_lshl_b64 s[14:15], s[4:5], 13
	v_writelane_b32 v253, s5, 29
	v_lshlrev_b32_e32 v42, 2, v2
	v_lshlrev_b32_e32 v43, 2, v6
	v_lshlrev_b32_e32 v44, 2, v8
	v_mov_b32_e32 v45, 0x358637bd
	s_mov_b32 s2, 0xf800000
	v_mov_b32_e32 v46, 0x260
	global_load_dwordx4 v[90:93], v[34:35], off offset:2048
	global_load_dwordx4 v[94:97], v[34:35], off offset:2064
	global_load_dwordx4 v[98:101], v[36:37], off
	global_load_dwordx4 v[102:105], v[36:37], off offset:16
	global_load_dwordx4 v[106:109], v[38:39], off
	global_load_dwordx4 v[110:113], v[38:39], off offset:16
	s_branch .LBB0_253
.LBB0_251:
	global_load_dwordx4 v[14:17], v42, s[10:11] nt
	global_load_dwordx4 v[10:13], v42, s[10:11] offset:16 nt
	global_load_dwordx4 v[26:29], v42, s[10:11] offset:2048 nt
	global_load_dwordx4 v[18:21], v42, s[10:11] offset:2064 nt
	global_load_dwordx4 v[6:9], v44, s[10:11] nt
	global_load_dwordx4 v[22:25], v43, s[10:11] offset:16 nt
	global_load_dwordx4 v[30:33], v43, s[10:11] nt
	global_load_dwordx4 v[2:5], v44, s[10:11] offset:16 nt
	global_load_dwordx4 v[48:51], v[34:35], off offset:16
	global_load_dwordx4 v[52:55], v[34:35], off
	s_waitcnt vmcnt(9)
	v_pk_mul_f32 v[56:57], v[16:17], v[16:17]
	v_pk_mul_f32 v[58:59], v[14:15], v[14:15]
	s_waitcnt vmcnt(8)
	v_pk_mul_f32 v[60:61], v[12:13], v[12:13]
	v_pk_mul_f32 v[62:63], v[10:11], v[10:11]
	s_waitcnt vmcnt(7)
	v_pk_mul_f32 v[64:65], v[28:29], v[28:29]
	v_pk_mul_f32 v[66:67], v[26:27], v[26:27]
	s_waitcnt vmcnt(6)
	v_pk_mul_f32 v[68:69], v[20:21], v[20:21]
	v_pk_mul_f32 v[70:71], v[18:19], v[18:19]
	v_pk_mov_b32 v[84:85], v[58:59], v[56:57] op_sel:[1,0]
	v_mov_b32_e32 v59, v57
	v_mov_b32_e32 v56, v60
	v_mov_b32_e32 v57, v62
	v_mov_b32_e32 v62, v61
	v_pk_mov_b32 v[60:61], v[66:67], v[64:65] op_sel:[1,0]
	v_mov_b32_e32 v67, v65
	s_waitcnt vmcnt(4)
	v_mov_b32_e32 v74, v23
	v_mov_b32_e32 v75, v7
	s_waitcnt vmcnt(3)
	v_mul_f32_e32 v76, v31, v31
	v_mul_f32_e32 v78, v33, v33
	v_mov_b32_e32 v64, v68
	v_mov_b32_e32 v65, v70
	v_mov_b32_e32 v70, v69
	v_pk_add_f32 v[58:59], v[84:85], v[58:59]
	v_pk_add_f32 v[60:61], v[60:61], v[66:67]
	v_mul_f32_e32 v47, v8, v8
	v_mul_f32_e32 v86, v9, v9
	v_pk_mul_f32 v[68:69], v[74:75], v[74:75]
	v_pk_fma_f32 v[74:75], v[30:31], v[30:31], v[76:77] op_sel_hi:[1,1,0]
	v_pk_fma_f32 v[76:77], v[32:33], v[32:33], v[78:79] op_sel_hi:[1,1,0]
	v_pk_add_f32 v[56:57], v[56:57], v[62:63]
	v_pk_add_f32 v[62:63], v[64:65], v[70:71]
	v_pk_add_f32 v[58:59], v[58:59], v[58:59] op_sel:[0,1] op_sel_hi:[1,0]
	v_pk_add_f32 v[60:61], v[60:61], v[60:61] op_sel:[0,1] op_sel_hi:[1,0]
	v_mov_b32_e32 v72, v22
	v_mov_b32_e32 v73, v6
	v_mov_b32_e32 v82, v25
	s_waitcnt vmcnt(2)
; __device__ __forceinline__ unsigned pk2(float lo, float hi) { const bfx2 b = __builtin_convertvector((f32x2){lo, hi}, bfx2); return __builtin_bit_cast(unsigned, b); }
; __device__ __forceinline__ void rms_row_to_bf16(const float* xrow, const float* g, bf16* orow, int lane) {
;     ...
;     for (int j = 0; j < 4; ++j) { const float* p = xrow + (j * 64 + lane) * 8; v[2 * j] = __builtin_nontemporal_load((const f32x4*)p); v[2 * j + 1] = __builtin_nontemporal_load((const f32x4*)(p + 4));
;         s += (v[2*j].x * v[2*j].x + v[2*j].y * v[2*j].y) + (v[2*j].z * v[2*j].z + v[2*j].w * v[2*j].w) + (v[2*j+1].x * v[2*j+1].x + v[2*j+1].y * v[2*j+1].y) + (v[2*j+1].z * v[2*j+1].z + v[2*j+1].w * v[2*j+1].w); }
;     const float r = 1.0f / sqrtf(wave_sum(s) * (1.0f / D) + RMS_EPS);
; #pragma unroll
;     for (int j = 0; j < 4; ++j) { const int c = (j * 64 + lane) * 8; const f32x4 g0 = *(const f32x4*)(g + c), g1 = *(const f32x4*)(g + c + 4); const f32x4 a = v[2 * j] * r * g0, b = v[2 * j + 1] * r * g1;
;         u32x4 o; o.x = pk2(a.x, a.y); o.y = pk2(a.z, a.w); o.z = pk2(b.x, b.y); o.w = pk2(b.z, b.w); *(u32x4*)(orow + c) = o; }
	v_mov_b32_e32 v83, v3
	v_mov_b32_e32 v75, v47
	v_mov_b32_e32 v77, v86
	v_pk_add_f32 v[58:59], v[56:57], v[58:59] op_sel:[1,0] op_sel_hi:[0,1]
	v_pk_add_f32 v[60:61], v[62:63], v[60:61] op_sel:[1,0] op_sel_hi:[0,1]
	v_mov_b32_e32 v80, v24
	v_mov_b32_e32 v81, v2
	v_pk_mul_f32 v[78:79], v[82:83], v[82:83]
	v_pk_fma_f32 v[64:65], v[72:73], v[72:73], v[68:69]
	v_pk_add_f32 v[68:69], v[74:75], v[76:77]
	v_pk_add_f32 v[56:57], v[56:57], v[58:59]
	v_pk_add_f32 v[58:59], v[62:63], v[60:61]
	v_pk_fma_f32 v[66:67], v[80:81], v[80:81], v[78:79]
	v_pk_add_f32 v[64:65], v[64:65], v[68:69]
	v_mul_f32_e32 v57, v4, v4
	v_mul_f32_e32 v59, v5, v5
	v_pk_add_f32 v[60:61], v[66:67], v[64:65]
	v_pk_add_f32 v[56:57], v[56:57], v[58:59]
	s_nop 0
	v_pk_add_f32 v[56:57], v[56:57], v[60:61]
	s_nop 0
	v_add_f32_e32 v47, v56, v57
	s_nop 1
	v_add_f32_dpp v47, v47, v47 quad_perm:[1,0,3,2] row_mask:0xf bank_mask:0xf bound_ctrl:1
	s_nop 1
	v_add_f32_dpp v47, v47, v47 quad_perm:[2,3,0,1] row_mask:0xf bank_mask:0xf bound_ctrl:1
	s_nop 1
	v_add_f32_dpp v47, v47, v47 row_half_mirror row_mask:0xf bank_mask:0xf bound_ctrl:1
	s_nop 1
	v_add_f32_dpp v47, v47, v47 row_mirror row_mask:0xf bank_mask:0xf bound_ctrl:1
	s_nop 0
	v_readlane_b32 s3, v47, 16
	v_readlane_b32 s8, v47, 48
	v_readlane_b32 s10, v47, 0
	v_readlane_b32 s11, v47, 32
	v_mov_b32_e32 v56, s3
	v_mov_b32_e32 v57, s8
	v_pk_add_f32 v[56:57], s[10:11], v[56:57]
	s_lshl_b64 s[10:11], s[4:5], 12
	v_add_f32_e32 v47, v56, v57
	v_fmamk_f32 v47, v47, 0x3a000000, v45
	v_mul_f32_e32 v56, 0x4f800000, v47
	v_cmp_gt_f32_e32 vcc, s2, v47
	s_nop 1
	v_cndmask_b32_e32 v47, v47, v56, vcc
	v_sqrt_f32_e32 v56, v47
	s_nop 0
	v_add_u32_e32 v57, -1, v56
	v_add_u32_e32 v58, 1, v56
	v_fma_f32 v59, -v57, v56, v47
	v_fma_f32 v60, -v58, v56, v47
	v_cmp_ge_f32_e64 s[4:5], 0, v59
	s_nop 1
	v_cndmask_b32_e64 v56, v56, v57, s[4:5]
	v_cmp_lt_f32_e64 s[4:5], 0, v60
	s_nop 1
	v_cndmask_b32_e64 v56, v56, v58, s[4:5]
	v_mul_f32_e32 v57, 0x37800000, v56
	v_cndmask_b32_e32 v56, v56, v57, vcc
	v_cmp_class_f32_e32 vcc, v47, v46
	s_nop 1
	v_cndmask_b32_e32 v47, v56, v47, vcc
	v_div_scale_f32 v58, s[4:5], v47, v47, 1.0
	v_rcp_f32_e32 v59, v58
	v_div_scale_f32 v60, vcc, 1.0, v47, 1.0
	v_lshl_add_u64 v[56:57], v[40:41], 0, s[10:11]
	v_fma_f32 v61, -v58, v59, 1.0
	v_fmac_f32_e32 v59, v61, v59
	v_mul_f32_e32 v61, v60, v59
	v_fma_f32 v62, -v58, v61, v60
	v_fmac_f32_e32 v61, v62, v59
	v_fma_f32 v58, -v58, v61, v60
	v_div_fmas_f32 v58, v58, v59, v61
	v_div_fixup_f32 v58, v58, v47, 1.0
	v_pk_mul_f32 v[14:15], v[14:15], v[58:59] op_sel_hi:[1,0]
	v_pk_mul_f32 v[16:17], v[16:17], v[58:59] op_sel_hi:[1,0]
	v_pk_mul_f32 v[10:11], v[10:11], v[58:59] op_sel_hi:[1,0]
	v_pk_mul_f32 v[12:13], v[12:13], v[58:59] op_sel_hi:[1,0]
	s_waitcnt vmcnt(0)
	v_pk_mul_f32 v[16:17], v[54:55], v[16:17]
	v_pk_mul_f32 v[14:15], v[52:53], v[14:15]
	v_pk_mul_f32 v[50:51], v[50:51], v[12:13]
	v_pk_mul_f32 v[12:13], v[48:49], v[10:11]
	v_cvt_pk_bf16_f32 v10, v14, v15
	v_cvt_pk_bf16_f32 v11, v16, v17
	v_cvt_pk_bf16_f32 v12, v12, v13
	v_cvt_pk_bf16_f32 v13, v50, v51
	global_store_dwordx4 v[56:57], v[10:13], off
	s_nop 0
	s_nop 0
	s_nop 0
	v_pk_mul_f32 v[26:27], v[26:27], v[58:59] op_sel_hi:[1,0]
	v_pk_mul_f32 v[28:29], v[28:29], v[58:59] op_sel_hi:[1,0]
	v_pk_mul_f32 v[18:19], v[18:19], v[58:59] op_sel_hi:[1,0]
	v_pk_mul_f32 v[20:21], v[20:21], v[58:59] op_sel_hi:[1,0]
	v_pk_mul_f32 v[22:23], v[22:23], v[58:59] op_sel_hi:[1,0]
	v_pk_mul_f32 v[24:25], v[24:25], v[58:59] op_sel_hi:[1,0]
	v_pk_mul_f32 v[6:7], v[6:7], v[58:59] op_sel_hi:[1,0]
	v_pk_mul_f32 v[8:9], v[8:9], v[58:59] op_sel_hi:[1,0]
	v_pk_mul_f32 v[2:3], v[2:3], v[58:59] op_sel_hi:[1,0]
	v_pk_mul_f32 v[4:5], v[4:5], v[58:59] op_sel_hi:[1,0]
	s_nop 1
	v_mov_b64_e32 v[10:11], v[90:91]
	v_mov_b64_e32 v[12:13], v[92:93]
	v_mov_b64_e32 v[14:15], v[94:95]
	v_mov_b64_e32 v[16:17], v[96:97]
	v_pk_mul_f32 v[12:13], v[12:13], v[28:29]
	v_pk_mul_f32 v[10:11], v[10:11], v[26:27]
	s_nop 0
	v_pk_mul_f32 v[16:17], v[16:17], v[20:21]
	v_pk_mul_f32 v[14:15], v[14:15], v[18:19]
	v_cvt_pk_bf16_f32 v10, v10, v11
	v_cvt_pk_bf16_f32 v11, v12, v13
	v_cvt_pk_bf16_f32 v12, v14, v15
	v_cvt_pk_bf16_f32 v13, v16, v17
	global_store_dwordx4 v[56:57], v[10:13], off offset:1024
	s_nop 0
	s_nop 0
	s_nop 0
	v_pk_mul_f32 v[18:19], v[30:31], v[58:59] op_sel_hi:[1,0]
	v_pk_mul_f32 v[20:21], v[32:33], v[58:59] op_sel_hi:[1,0]
	s_nop 1
	v_mov_b64_e32 v[10:11], v[98:99]
	v_mov_b64_e32 v[12:13], v[100:101]
	v_mov_b64_e32 v[14:15], v[102:103]
	v_mov_b64_e32 v[16:17], v[104:105]
	v_pk_mul_f32 v[10:11], v[10:11], v[18:19]
	v_pk_mul_f32 v[12:13], v[12:13], v[20:21]
	s_nop 0
	v_pk_mul_f32 v[16:17], v[16:17], v[24:25]
	v_pk_mul_f32 v[14:15], v[14:15], v[22:23]
	v_cvt_pk_bf16_f32 v10, v10, v11
	v_cvt_pk_bf16_f32 v11, v12, v13
	v_cvt_pk_bf16_f32 v12, v14, v15
	v_cvt_pk_bf16_f32 v13, v16, v17
	global_store_dwordx4 v[56:57], v[10:13], off offset:2048
	s_nop 0
	s_nop 0
	s_nop 0
	s_nop 1
	v_mov_b64_e32 v[10:11], v[106:107]
	v_mov_b64_e32 v[12:13], v[108:109]
	v_mov_b64_e32 v[14:15], v[110:111]
	v_mov_b64_e32 v[16:17], v[112:113]
	v_pk_mul_f32 v[8:9], v[8:9], v[12:13]
	v_pk_mul_f32 v[6:7], v[6:7], v[10:11]
	s_nop 0
	v_pk_mul_f32 v[10:11], v[4:5], v[16:17]
	v_pk_mul_f32 v[4:5], v[2:3], v[14:15]
	v_cvt_pk_bf16_f32 v2, v6, v7
	v_cvt_pk_bf16_f32 v3, v8, v9
	v_cvt_pk_bf16_f32 v4, v4, v5
	v_cvt_pk_bf16_f32 v5, v10, v11
	global_store_dwordx4 v[56:57], v[2:5], off offset:3072

; #define LAS __attribute__((address_space(3)))
; __device__ __forceinline__ unsigned pk2(float lo, float hi) { const bfx2 b = __builtin_convertvector((f32x2){lo, hi}, bfx2); return __builtin_bit_cast(unsigned, b); }
; __device__ __forceinline__ void loader_stage(Frame& F, const void* kp, const void* vp, int pitch, bool isf32, int nvalid, int lt, int boff) {
;     ...
;     for (int kv = 0; kv < 2; ++kv) { const void* sp = kv ? vp : kp; u32x2 r[8];
; #pragma unroll
;         for (int j = 0; j < 8; ++j) r[j] = (u32x2){0u, 0u};
;         if (key < nvalid) {
;             if (isf32) { const float* s = (const float*)sp + (size_t)key * pitch + 4 * ch; f32x4 a[8];
; #pragma unroll
;                 for (int j = 0; j < 8; ++j) a[j] = *(const f32x4*)(s + 16 * j);
; #pragma unroll
;                 for (int j = 0; j < 8; ++j) { r[j].x = pk2(a[j].x, a[j].y); r[j].y = pk2(a[j].z, a[j].w); } }
;             else { const bf16* s = (const bf16*)sp + (size_t)key * pitch + 4 * ch;
; #pragma unroll
;                 for (int j = 0; j < 8; ++j) r[j] = *(const u32x2*)(s + 16 * j); } }
;         if (kv == 0) { LAS unsigned char* kd = F.lds + A_KT + boff + key * KT_PITCH + 8 * ch;
; #pragma unroll
;             for (int j = 0; j < 8; ++j) *(LAS u32x2*)(kd + 32 * j) = r[j]; }
.LBB0_2093:
	s_andn2_b64 vcc, exec, s[6:7]
	s_cbranch_vccnz .LBB0_2095
	v_lshl_add_u64 v[10:11], v[8:9], 2, v[10:11]
	v_lshlrev_b32_e32 v2, 2, v110
	v_lshl_add_u64 v[10:11], v[10:11], 0, v[2:3]
	global_load_dwordx4 v[12:15], v[10:11], off
	global_load_dwordx4 v[100:103], v[10:11], off offset:64
	global_load_dwordx4 v[104:107], v[10:11], off offset:128
	global_load_dwordx4 v[112:115], v[10:11], off offset:192
	global_load_dwordx4 v[116:119], v[10:11], off offset:256
	global_load_dwordx4 v[120:123], v[10:11], off offset:320
	global_load_dwordx4 v[124:127], v[10:11], off offset:384
	global_load_dwordx4 v[128:131], v[10:11], off offset:448
	v_lshl_add_u64 v[18:19], v[8:9], 2, v[4:5]
	v_lshl_add_u64 v[18:19], v[18:19], 0, v[2:3]
	global_load_dwordx4 v[20:23], v[18:19], off
	global_load_dwordx4 v[24:27], v[18:19], off offset:64
	global_load_dwordx4 v[28:31], v[18:19], off offset:128
	global_load_dwordx4 v[32:35], v[18:19], off offset:192
	global_load_dwordx4 v[36:39], v[18:19], off offset:256
	global_load_dwordx4 v[40:43], v[18:19], off offset:320
	global_load_dwordx4 v[44:47], v[18:19], off offset:384
	global_load_dwordx4 v[48:51], v[18:19], off offset:448
	s_waitcnt vmcnt(15)
	v_cvt_pk_bf16_f32 v12, v12, v13
	v_cvt_pk_bf16_f32 v13, v14, v15
	s_waitcnt vmcnt(14)
	v_cvt_pk_bf16_f32 v100, v100, v101
	v_cvt_pk_bf16_f32 v101, v102, v103
	s_waitcnt vmcnt(13)
	v_cvt_pk_bf16_f32 v14, v104, v105
	v_cvt_pk_bf16_f32 v15, v106, v107
	s_waitcnt vmcnt(12)
	v_cvt_pk_bf16_f32 v102, v112, v113
	v_cvt_pk_bf16_f32 v103, v114, v115
	s_waitcnt vmcnt(11)
	v_cvt_pk_bf16_f32 v16, v116, v117
	v_cvt_pk_bf16_f32 v17, v118, v119
	s_waitcnt vmcnt(10)
	v_cvt_pk_bf16_f32 v104, v120, v121
	v_cvt_pk_bf16_f32 v105, v122, v123
	s_waitcnt vmcnt(9)
	v_cvt_pk_bf16_f32 v98, v124, v125
	v_cvt_pk_bf16_f32 v99, v126, v127
	s_waitcnt vmcnt(8)
	v_cvt_pk_bf16_f32 v106, v128, v129
	v_cvt_pk_bf16_f32 v107, v130, v131
	s_or_b64 exec, exec, s[70:71]
	s_bitcmp1_b32 s26, 0
	s_cselect_b32 s6, 0x19f00, 0
	v_mul_lo_u32 v2, v109, s54
	v_lshlrev_b32_e32 v7, 3, v108
	s_add_i32 s26, s6, 0
	v_add3_u32 v2, s26, v2, v7
	ds_write2_b64 v2, v[12:13], v[100:101] offset1:4
	ds_write2_b64 v2, v[14:15], v[102:103] offset0:8 offset1:12
	ds_write2_b64 v2, v[16:17], v[104:105] offset0:16 offset1:20
	ds_write2_b64 v2, v[98:99], v[106:107] offset0:24 offset1:28
	s_branch .Lattn_ld_kwdone

; __device__ __forceinline__ unsigned pk2(float lo, float hi) { const bfx2 b = __builtin_convertvector((f32x2){lo, hi}, bfx2); return __builtin_bit_cast(unsigned, b); }
; __device__ __forceinline__ void loader_stage(Frame& F, const void* kp, const void* vp, int pitch, bool isf32, int nvalid, int lt, int boff) {
;     ...
;     for (int kv = 0; kv < 2; ++kv) { const void* sp = kv ? vp : kp; u32x2 r[8];
; #pragma unroll
;         for (int j = 0; j < 8; ++j) r[j] = (u32x2){0u, 0u};
;         if (key < nvalid) {
;             if (isf32) { const float* s = (const float*)sp + (size_t)key * pitch + 4 * ch; f32x4 a[8];
; #pragma unroll
;                 for (int j = 0; j < 8; ++j) a[j] = *(const f32x4*)(s + 16 * j);
; #pragma unroll
;                 for (int j = 0; j < 8; ++j) { r[j].x = pk2(a[j].x, a[j].y); r[j].y = pk2(a[j].z, a[j].w); } }
;             else { const bf16* s = (const bf16*)sp + (size_t)key * pitch + 4 * ch;
; #pragma unroll
;                 for (int j = 0; j < 8; ++j) r[j] = *(const u32x2*)(s + 16 * j); } }
.Lattn_ld_kwdone:
	v_mov_b32_e32 v7, 0
	v_mov_b32_e32 v102, 0
	v_mov_b32_e32 v103, 0
	v_mov_b32_e32 v100, 0
	v_mov_b32_e32 v101, 0
	v_mov_b32_e32 v98, 0
	v_mov_b32_e32 v99, 0
	v_mov_b32_e32 v16, 0
	v_mov_b32_e32 v17, 0
	v_mov_b32_e32 v14, 0
	v_mov_b32_e32 v15, 0
	v_mov_b32_e32 v12, 0
	v_mov_b32_e32 v13, 0
	v_mov_b32_e32 v10, 0
	v_mov_b32_e32 v11, 0
	s_and_saveexec_b64 s[70:71], s[10:11]
	s_cbranch_execz .LBB0_2100
	s_andn2_b64 vcc, exec, s[46:47]
	s_mov_b64 s[6:7], -1
	s_cbranch_vccnz .LBB0_2098
	v_lshl_add_u64 v[6:7], v[8:9], 1, v[4:5]
	v_lshlrev_b32_e32 v2, 1, v110
	v_lshl_add_u64 v[10:11], v[6:7], 0, v[2:3]
	global_load_dwordx2 v[6:7], v[10:11], off
	global_load_dwordx2 v[102:103], v[10:11], off offset:32
	global_load_dwordx2 v[100:101], v[10:11], off offset:64
	global_load_dwordx2 v[98:99], v[10:11], off offset:96
	global_load_dwordx2 v[16:17], v[10:11], off offset:128
	global_load_dwordx2 v[14:15], v[10:11], off offset:160
	global_load_dwordx2 v[12:13], v[10:11], off offset:192
	s_nop 0
	global_load_dwordx2 v[10:11], v[10:11], off offset:224
	s_mov_b64 s[6:7], 0
.LBB0_2098:
	s_andn2_b64 vcc, exec, s[6:7]
	s_cbranch_vccnz .LBB0_2100
	s_waitcnt vmcnt(7)
	v_cvt_pk_bf16_f32 v6, v20, v21
	v_cvt_pk_bf16_f32 v7, v22, v23
	s_waitcnt vmcnt(6)
	v_cvt_pk_bf16_f32 v102, v24, v25
	v_cvt_pk_bf16_f32 v103, v26, v27
	s_waitcnt vmcnt(5)
	v_cvt_pk_bf16_f32 v100, v28, v29
	v_cvt_pk_bf16_f32 v101, v30, v31
	s_waitcnt vmcnt(4)
	v_cvt_pk_bf16_f32 v98, v32, v33
	v_cvt_pk_bf16_f32 v99, v34, v35
	s_waitcnt vmcnt(3)
	v_cvt_pk_bf16_f32 v16, v36, v37
	v_cvt_pk_bf16_f32 v17, v38, v39
	s_waitcnt vmcnt(2)
	v_cvt_pk_bf16_f32 v14, v40, v41
	v_cvt_pk_bf16_f32 v15, v42, v43
	s_waitcnt vmcnt(1)
	v_cvt_pk_bf16_f32 v12, v44, v45
	v_cvt_pk_bf16_f32 v13, v46, v47
	s_waitcnt vmcnt(0)
	v_cvt_pk_bf16_f32 v10, v48, v49
	v_cvt_pk_bf16_f32 v11, v50, v51
